# GLA output units: the 24 fragment ds_read_b128 of the 12-MFMA accumulation chain issued ahead (12 in flight) instead of one LDS round trip per MFMA
# speedup vs baseline: 1.0060x; 1.0018x over previous
; #define LAS __attribute__((address_space(3)))
; __device__ __forceinline__ float bflo(unsigned w) { return __uint_as_float(w << 16); }
; __device__ __forceinline__ float bfhi(unsigned w) { return __uint_as_float(w & 0xffff0000u); }
; __device__ __forceinline__ unsigned cvt_pk_bf16(float lo, float hi) { unsigned r; asm volatile("v_cvt_pk_bf16_f32 %0, %1, %2" : "=v"(r) : "v"(lo), "v"(hi)); return r; }
; __device__ __forceinline__ float silu_f(float g) { return g * __builtin_amdgcn_rcpf(1.f + __expf(-g)); }
; __device__ __forceinline__ int crow16(int r, int hi) { return (r & 3) + 8 * (r >> 2) + 4 * hi; }
; __device__ __forceinline__ void gla_p3(CArgs& a, int l, int cc, int h, LAS float* L) {
;     ...
;     { const int ib = wid >> 2, eb = wid & 3; f32x16 acc = {};
; #pragma unroll
;       for (int ks = 0; ks < 4; ++ks) {
;           acc = __builtin_amdgcn_mfma_f32_32x32x16_bf16(ldfrag(B + GB_ATT, 32 * ib + r32, ks, hi), ldfrag(B + GB_VT, 32 * eb + r32, ks, hi), acc, 0, 0, 0);
;           acc = __builtin_amdgcn_mfma_f32_32x32x16_bf16(ldfrag(B + GB_QDF, 32 * ib + r32, ks, hi), ldfrag(B + GB_SFT, 32 * eb + r32, ks, hi), acc, 0, 0, 0);
;           acc = __builtin_amdgcn_mfma_f32_32x32x16_bf16(ldfrag(B + GB_QDB, 32 * ib + r32, ks, hi), ldfrag(B + GB_SBT, 32 * eb + r32, ks, hi), acc, 0, 0, 0); }
; #pragma unroll
;       for (int r = 0; r < 16; ++r) L[(32 * ib + crow16(r, hi)) * 128 + 32 * eb + r32] = acc[r]; }
;     __syncthreads();
;     const int i0 = (tid >> 5) * 4, e4 = (tid & 31) * 4;
;     bf16_t* Z = (bf16_t*)(a.ws + WS_HZ);
;     const f32x4 gn = *(const f32x4*)(a.in[I_CON] + l * 128 + e4);
; #pragma unroll
;     for (int r = 0; r < 4; ++r) { const f32x4 o = *(const LAS f32x4*)(L + (i0 + r) * 128 + e4);
;         float ss = (o.x * o.x + o.y * o.y) + (o.z * o.z + o.w * o.w);
; #pragma unroll
;         for (int m = 1; m < 32; m <<= 1) ss += __shfl_xor(ss, m);
;         const float rs = rsqrtf(ss * (1.f / 128.f) + EPS);
;         const size_t row = (size_t)cc * 64 + i0 + r;
;         const u32x2 gw = *(const u32x2*)(P + (size_t)(i0 + r) * INP + C_CG + h * 128 + e4);
;         const f32x4 y = o * rs * gn;
;         u32x2 w; w.x = cvt_pk_bf16(y.x * silu_f(bflo(gw.x)), y.y * silu_f(bfhi(gw.x))); w.y = cvt_pk_bf16(y.z * silu_f(bflo(gw.y)), y.w * silu_f(bfhi(gw.y)));
;         *(u32x2*)(Z + row * DM + 1536 + h * 128 + e4) = w; }
.LBB0_96:
	s_or_b64 exec, exec, s[42:43]
	v_ashrrev_i32_e32 v38, 8, v34
	v_lshl_or_b32 v2, v38, 5, v36
	s_movk_i32 s5, 0x90
	v_mul_lo_u32 v10, v2, s5
	s_add_i32 s5, 0, 0x15a00
	v_add3_u32 v30, s5, v10, v37
	s_waitcnt lgkmcnt(0)
	s_barrier
	v_bfe_u32 v39, v34, 6, 2
	v_lshl_or_b32 v6, v39, 5, v36
	v_mul_u32_u24_e32 v31, 0x90, v6
	v_add3_u32 v40, s17, v31, v37
	v_add3_u32 v41, 0, v10, v37
	s_add_i32 s5, 0, 0x17e00
	v_add3_u32 v42, s5, v31, v37
	s_add_i32 s5, 0, 0x1c600
	v_add3_u32 v37, s5, v31, v37
	ds_read_b128 v[76:79], v30
	ds_read_b128 v[80:83], v40
	ds_read_b128 v[84:87], v41 offset:33280
	ds_read_b128 v[88:91], v42
	ds_read_b128 v[92:95], v41 offset:42496
	ds_read_b128 v[96:99], v37
	ds_read_b128 v[100:103], v30 offset:32
	ds_read_b128 v[104:107], v40 offset:32
	ds_read_b128 v[108:111], v41 offset:33312
	ds_read_b128 v[112:115], v42 offset:32
	ds_read_b128 v[116:119], v41 offset:42528
	ds_read_b128 v[120:123], v37 offset:32
	s_waitcnt lgkmcnt(10)
	v_mfma_f32_32x32x16_bf16 v[2:17], v[76:79], v[80:83], 0
	ds_read_b128 v[124:127], v30 offset:64
	ds_read_b128 v[128:131], v40 offset:64
	s_waitcnt lgkmcnt(10)
	v_mfma_f32_32x32x16_bf16 v[2:17], v[84:87], v[88:91], v[2:17]
	ds_read_b128 v[132:135], v41 offset:33344
	ds_read_b128 v[136:139], v42 offset:64
	s_waitcnt lgkmcnt(10)
	v_mfma_f32_32x32x16_bf16 v[2:17], v[92:95], v[96:99], v[2:17]
	ds_read_b128 v[140:143], v41 offset:42560
	ds_read_b128 v[144:147], v37 offset:64
	s_waitcnt lgkmcnt(10)
	v_mfma_f32_32x32x16_bf16 v[2:17], v[100:103], v[104:107], v[2:17]
	ds_read_b128 v[148:151], v30 offset:96
	ds_read_b128 v[152:155], v40 offset:96
	s_waitcnt lgkmcnt(10)
	v_mfma_f32_32x32x16_bf16 v[2:17], v[108:111], v[112:115], v[2:17]
	ds_read_b128 v[156:159], v41 offset:33376
	ds_read_b128 v[160:163], v42 offset:96
	s_waitcnt lgkmcnt(10)
	v_mfma_f32_32x32x16_bf16 v[2:17], v[116:119], v[120:123], v[2:17]
	ds_read_b128 v[164:167], v41 offset:42592
	ds_read_b128 v[168:171], v37 offset:96
	v_and_b32_e32 v0, 0x7c, v0
	s_lshl_b32 s18, s4, 1
	s_ashr_i32 s23, s22, 31
	s_lshl_b64 s[4:5], s[22:23], 18
	s_add_u32 s4, s56, s4
	s_addc_u32 s5, s57, s5
	v_lshlrev_b32_e32 v19, 11, v35
	v_ashrrev_i32_e32 v20, 3, v34
	v_lshlrev_b32_e32 v34, 14, v38
	v_lshlrev_b32_e32 v21, 2, v36
	v_lshlrev_b32_e32 v35, 7, v39
	v_and_b32_e32 v18, -4, v20
	v_lshlrev_b32_e32 v36, 2, v0
	v_lshlrev_b32_e32 v0, 1, v0
	v_add3_u32 v30, 0, v34, v19
	v_add3_u32 v21, v30, v35, v21
	v_ashrrev_i32_e32 v19, 31, v18
	v_lshlrev_b64 v[26:27], 13, v[18:19]
	v_lshl_add_u64 v[26:27], s[20:21], 0, v[26:27]
	v_lshl_add_u64 v[26:27], v[26:27], 0, s[18:19]
	v_lshl_add_u64 v[26:27], v[26:27], 0, v[0:1]
	s_waitcnt lgkmcnt(10)
	v_mfma_f32_32x32x16_bf16 v[2:17], v[124:127], v[128:131], v[2:17]
	s_waitcnt lgkmcnt(8)
	v_mfma_f32_32x32x16_bf16 v[2:17], v[132:135], v[136:139], v[2:17]
	s_waitcnt lgkmcnt(6)
	v_mfma_f32_32x32x16_bf16 v[2:17], v[140:143], v[144:147], v[2:17]
	s_waitcnt lgkmcnt(4)
	v_mfma_f32_32x32x16_bf16 v[2:17], v[148:151], v[152:155], v[2:17]
	s_waitcnt lgkmcnt(2)
	v_mfma_f32_32x32x16_bf16 v[2:17], v[156:159], v[160:163], v[2:17]
	v_add_co_u32_e32 v26, vcc, s10, v26
	s_waitcnt lgkmcnt(0)
	v_mfma_f32_32x32x16_bf16 v[2:17], v[164:167], v[168:171], v[2:17]
	v_addc_co_u32_e32 v27, vcc, 0, v27, vcc
	s_nop 10
	ds_write2st64_b32 v21, v2, v3 offset1:2
	ds_write2st64_b32 v21, v4, v5 offset0:4 offset1:6
	ds_write2st64_b32 v21, v6, v7 offset0:16 offset1:18
	ds_write2st64_b32 v21, v8, v9 offset0:20 offset1:22
	ds_write2st64_b32 v21, v10, v11 offset0:32 offset1:34
	ds_write2st64_b32 v21, v12, v13 offset0:36 offset1:38
	ds_write2st64_b32 v21, v14, v15 offset0:48 offset1:50
	ds_write2st64_b32 v21, v16, v17 offset0:52 offset1:54
	s_waitcnt lgkmcnt(0)
	s_barrier
	global_load_dwordx2 v[10:11], v[26:27], off offset:2688
	global_load_dwordx4 v[2:5], v36, s[52:53]
	v_add_co_u32_e32 v76, vcc, 0x2000, v26
	s_nop 1
	v_addc_co_u32_e32 v77, vcc, 0, v27, vcc
	global_load_dwordx2 v[80:81], v[76:77], off offset:2688
	v_add_co_u32_e32 v76, vcc, 0x2000, v76
	s_nop 1
	v_addc_co_u32_e32 v77, vcc, 0, v77, vcc
	global_load_dwordx2 v[82:83], v[76:77], off offset:2688
	v_add_co_u32_e32 v76, vcc, 0x2000, v76
	s_nop 1
	v_addc_co_u32_e32 v77, vcc, 0, v77, vcc
	global_load_dwordx2 v[84:85], v[76:77], off offset:2688
	v_add_u32_e32 v22, 0, v36
	v_lshl_add_u32 v6, v18, 9, v22
	ds_read_b128 v[6:9], v6
	v_and_b32_e32 v12, 64, v223
	v_xor_b32_e32 v13, 1, v223
	v_add_u32_e32 v25, 64, v12
	v_cmp_lt_i32_e32 vcc, v13, v25
	s_waitcnt lgkmcnt(0)
	v_pk_mul_f32 v[14:15], v[6:7], v[6:7]
	v_xor_b32_e32 v23, 2, v223
	v_cndmask_b32_e32 v12, v223, v13, vcc
	v_lshlrev_b32_e32 v21, 2, v12
	v_pk_mul_f32 v[12:13], v[8:9], v[8:9]
	v_cmp_lt_i32_e32 vcc, v23, v25
	v_pk_mov_b32 v[16:17], v[14:15], v[12:13] op_sel:[1,0]
	v_mov_b32_e32 v15, v13
	v_pk_add_f32 v[12:13], v[16:17], v[14:15]
	v_cndmask_b32_e32 v15, v223, v23, vcc
	v_add_f32_e32 v12, v12, v13
	ds_bpermute_b32 v13, v21, v12
	v_lshlrev_b32_e32 v23, 2, v15
	v_xor_b32_e32 v24, 4, v223
	v_cmp_lt_i32_e32 vcc, v24, v25
	v_xor_b32_e32 v14, 8, v223
	s_waitcnt lgkmcnt(0)
	v_add_f32_e32 v12, v12, v13
	ds_bpermute_b32 v13, v23, v12
	v_cndmask_b32_e32 v16, v223, v24, vcc
	v_lshlrev_b32_e32 v24, 2, v16
	v_cmp_lt_i32_e64 s[40:41], v14, v25
	v_xor_b32_e32 v15, 16, v223
	s_waitcnt lgkmcnt(0)
	v_add_f32_e32 v12, v12, v13
	s_nop 1
	v_cndmask_b32_e64 v14, v223, v14, s[40:41]
	v_cmp_lt_i32_e32 vcc, v15, v25
	v_lshlrev_b32_e32 v25, 2, v14
	v_add_f32_dpp v14, v12, v12 row_half_mirror row_mask:0xf bank_mask:0xf
	ds_bpermute_b32 v16, v25, v14
	v_cndmask_b32_e32 v15, v223, v15, vcc
	v_lshlrev_b32_e32 v26, 2, v15
	v_or_b32_e32 v12, 1, v18
	v_ashrrev_i32_e32 v13, 31, v12
	s_waitcnt lgkmcnt(0)
; #define LAS __attribute__((address_space(3)))
; __device__ __forceinline__ float bflo(unsigned w) { return __uint_as_float(w << 16); }
; __device__ __forceinline__ float bfhi(unsigned w) { return __uint_as_float(w & 0xffff0000u); }
; __device__ __forceinline__ unsigned cvt_pk_bf16(float lo, float hi) { unsigned r; asm volatile("v_cvt_pk_bf16_f32 %0, %1, %2" : "=v"(r) : "v"(lo), "v"(hi)); return r; }
; __device__ __forceinline__ float silu_f(float g) { return g * __builtin_amdgcn_rcpf(1.f + __expf(-g)); }
; __device__ __forceinline__ void gla_p3(CArgs& a, int l, int cc, int h, LAS float* L) {
;     ...
;     const int i0 = (tid >> 5) * 4, e4 = (tid & 31) * 4;
;     bf16_t* Z = (bf16_t*)(a.ws + WS_HZ);
;     const f32x4 gn = *(const f32x4*)(a.in[I_CON] + l * 128 + e4);
; #pragma unroll
;     for (int r = 0; r < 4; ++r) { const f32x4 o = *(const LAS f32x4*)(L + (i0 + r) * 128 + e4);
;         float ss = (o.x * o.x + o.y * o.y) + (o.z * o.z + o.w * o.w);
; #pragma unroll
;         for (int m = 1; m < 32; m <<= 1) ss += __shfl_xor(ss, m);
;         const float rs = rsqrtf(ss * (1.f / 128.f) + EPS);
;         const size_t row = (size_t)cc * 64 + i0 + r;
;         const u32x2 gw = *(const u32x2*)(P + (size_t)(i0 + r) * INP + C_CG + h * 128 + e4);
;         const f32x4 y = o * rs * gn;
;         u32x2 w; w.x = cvt_pk_bf16(y.x * silu_f(bflo(gw.x)), y.y * silu_f(bfhi(gw.x))); w.y = cvt_pk_bf16(y.z * silu_f(bflo(gw.y)), y.w * silu_f(bfhi(gw.y)));
;         *(u32x2*)(Z + row * DM + 1536 + h * 128 + e4) = w; }
	v_add_f32_e32 v16, v14, v16
	ds_bpermute_b32 v17, v26, v16
	v_lshlrev_b64 v[14:15], 13, v[12:13]
	v_lshl_add_u64 v[14:15], s[20:21], 0, v[14:15]
	v_lshl_add_u64 v[14:15], v[14:15], 0, s[18:19]
	v_lshl_add_u64 v[14:15], v[14:15], 0, v[0:1]
	s_waitcnt lgkmcnt(0)
	v_add_f32_e32 v13, v16, v17
	v_fmamk_f32 v13, v13, 0x3c000000, v216
	v_cmp_gt_f32_e32 vcc, s26, v13
	v_mul_f32_e32 v16, 0x4b800000, v13
	s_nop 0
	v_cndmask_b32_e32 v13, v13, v16, vcc
	v_rsq_f32_e32 v13, v13
	v_add_co_u32_e64 v16, s[40:41], s10, v14
	v_mul_f32_e32 v14, 0x45800000, v13
	v_cndmask_b32_e32 v14, v13, v14, vcc
	v_pk_mul_f32 v[6:7], v[6:7], v[14:15] op_sel_hi:[1,0]
	v_pk_mul_f32 v[8:9], v[8:9], v[14:15] op_sel_hi:[1,0]
	v_addc_co_u32_e64 v17, s[40:41], 0, v15, s[40:41]
	s_waitcnt vmcnt(1)
	v_lshlrev_b32_e32 v13, 16, v10
	v_and_b32_e32 v10, 0xffff0000, v10
	v_lshlrev_b32_e32 v14, 16, v11
	v_and_b32_e32 v11, 0xffff0000, v11
	v_mul_f32_e32 v15, 0xbfb8aa3b, v13
	v_mul_f32_e32 v27, 0xbfb8aa3b, v10
	v_mul_f32_e32 v28, 0xbfb8aa3b, v14
	v_mul_f32_e32 v29, 0xbfb8aa3b, v11
	v_exp_f32_e32 v15, v15
	v_exp_f32_e32 v27, v27
	v_exp_f32_e32 v28, v28
	v_exp_f32_e32 v29, v29
	v_add_f32_e32 v15, 1.0, v15
	v_add_f32_e32 v27, 1.0, v27
	v_add_f32_e32 v28, 1.0, v28
	v_add_f32_e32 v29, 1.0, v29
	v_rcp_f32_e32 v15, v15
	v_rcp_f32_e32 v27, v27
	v_rcp_f32_e32 v28, v28
	v_rcp_f32_e32 v29, v29
	s_waitcnt vmcnt(0)
	v_pk_mul_f32 v[8:9], v[4:5], v[8:9]
	v_pk_mul_f32 v[6:7], v[2:3], v[6:7]
	v_mul_f32_e32 v13, v15, v13
	v_mul_f32_e32 v10, v27, v10
	v_mul_f32_e32 v14, v28, v14
	v_mul_f32_e32 v11, v29, v11
	v_mul_f32_e32 v6, v13, v6
	v_mul_f32_e32 v7, v10, v7
	v_mul_f32_e32 v8, v14, v8
	v_mul_f32_e32 v9, v11, v9
	v_cvt_pk_bf16_f32 v14, v6, v7
	v_cvt_pk_bf16_f32 v15, v8, v9
	v_mov_b64_e32 v[16:17], v[80:81]
	v_lshl_add_u32 v6, v12, 9, v22
	ds_read_b128 v[6:9], v6
	s_waitcnt lgkmcnt(0)
	v_pk_mul_f32 v[10:11], v[8:9], v[8:9]
	v_pk_mul_f32 v[12:13], v[6:7], v[6:7]
	s_nop 0
	v_pk_mov_b32 v[28:29], v[12:13], v[10:11] op_sel:[1,0]
	v_mov_b32_e32 v13, v11
	v_pk_add_f32 v[10:11], v[28:29], v[12:13]
	v_or_b32_e32 v12, 2, v18
	v_add_f32_e32 v10, v10, v11
	s_nop 1
	v_ashrrev_i32_e32 v13, 31, v12
	v_add_f32_dpp v27, v10, v10 quad_perm:[1,0,3,2] row_mask:0xf bank_mask:0xf
	ds_bpermute_b32 v28, v23, v27
	v_lshlrev_b64 v[10:11], 12, v[18:19]
	v_lshlrev_b64 v[18:19], 13, v[12:13]
	v_lshl_add_u64 v[10:11], s[4:5], 0, v[10:11]
	v_lshl_add_u64 v[10:11], v[10:11], 0, s[18:19]
	s_waitcnt lgkmcnt(0)
	v_add_f32_e32 v27, v27, v28
	ds_bpermute_b32 v28, v24, v27
	v_lshl_add_u64 v[10:11], v[10:11], 0, v[0:1]
	s_mov_b32 s4, 0xb900000
	v_lshl_add_u64 v[18:19], s[20:21], 0, v[18:19]
	v_lshl_add_u64 v[18:19], v[18:19], 0, s[18:19]
	s_waitcnt lgkmcnt(0)
	v_add_f32_e32 v13, v27, v28
	ds_bpermute_b32 v27, v25, v13
	v_add_co_u32_e32 v28, vcc, s4, v10
	v_lshl_add_u64 v[18:19], v[18:19], 0, v[0:1]
	s_nop 0
	v_addc_co_u32_e32 v29, vcc, 0, v11, vcc
	s_waitcnt lgkmcnt(0)
	v_add_f32_e32 v13, v13, v27
	v_mov_b32_e32 v27, v13
	global_store_dwordx2 v[28:29], v[14:15], off offset:3072
	v_add_co_u32_e32 v18, vcc, s10, v18
	s_mov_b32 s4, 0xb901000
	s_nop 1
	v_permlane16_swap_b32_e32 v13, v27
	v_add_f32_e32 v13, v13, v27
	v_fmamk_f32 v13, v13, 0x3c000000, v216
	v_cmp_gt_f32_e64 s[40:41], s26, v13
	v_mul_f32_e32 v27, 0x4b800000, v13
	v_addc_co_u32_e32 v19, vcc, 0, v19, vcc
	v_cndmask_b32_e64 v13, v13, v27, s[40:41]
	v_rsq_f32_e32 v13, v13
	s_nop 0
	v_mul_f32_e32 v14, 0x45800000, v13
	v_cndmask_b32_e64 v14, v13, v14, s[40:41]
	v_pk_mul_f32 v[6:7], v[6:7], v[14:15] op_sel_hi:[1,0]
	v_pk_mul_f32 v[8:9], v[8:9], v[14:15] op_sel_hi:[1,0]
	v_pk_mul_f32 v[6:7], v[2:3], v[6:7]
	v_pk_mul_f32 v[8:9], v[4:5], v[8:9]
	s_waitcnt vmcnt(1)
	v_lshlrev_b32_e32 v13, 16, v16
	v_and_b32_e32 v14, 0xffff0000, v16
	v_and_b32_e32 v16, 0xffff0000, v17
	v_lshlrev_b32_e32 v15, 16, v17
	v_mul_f32_e32 v29, 0xbfb8aa3b, v16
	v_mul_f32_e32 v17, 0xbfb8aa3b, v13
	v_mul_f32_e32 v27, 0xbfb8aa3b, v14
	v_mul_f32_e32 v28, 0xbfb8aa3b, v15
	v_exp_f32_e32 v29, v29
	v_exp_f32_e32 v17, v17
	v_exp_f32_e32 v27, v27
	v_exp_f32_e32 v28, v28
	v_add_f32_e32 v29, 1.0, v29
	v_add_f32_e32 v17, 1.0, v17
	v_add_f32_e32 v27, 1.0, v27
	v_add_f32_e32 v28, 1.0, v28
	v_rcp_f32_e32 v29, v29
	v_rcp_f32_e32 v17, v17
	v_rcp_f32_e32 v27, v27
	v_rcp_f32_e32 v28, v28
	v_mul_f32_e32 v16, v29, v16
	v_mul_f32_e32 v13, v17, v13
	v_mul_f32_e32 v14, v27, v14
	v_mul_f32_e32 v15, v28, v15
	v_mul_f32_e32 v9, v16, v9
	v_mul_f32_e32 v6, v13, v6
	v_mul_f32_e32 v7, v14, v7
	v_mul_f32_e32 v13, v15, v8
	v_cvt_pk_bf16_f32 v8, v6, v7
	v_cvt_pk_bf16_f32 v9, v13, v9
	v_mov_b64_e32 v[16:17], v[82:83]
	v_lshl_add_u32 v6, v12, 9, v22
	ds_read_b128 v[12:15], v6
	s_waitcnt lgkmcnt(0)
; #define LAS __attribute__((address_space(3)))
; __device__ __forceinline__ float bflo(unsigned w) { return __uint_as_float(w << 16); }
; __device__ __forceinline__ float bfhi(unsigned w) { return __uint_as_float(w & 0xffff0000u); }
; __device__ __forceinline__ unsigned cvt_pk_bf16(float lo, float hi) { unsigned r; asm volatile("v_cvt_pk_bf16_f32 %0, %1, %2" : "=v"(r) : "v"(lo), "v"(hi)); return r; }
; __device__ __forceinline__ float silu_f(float g) { return g * __builtin_amdgcn_rcpf(1.f + __expf(-g)); }
; __device__ __forceinline__ void gla_p3(CArgs& a, int l, int cc, int h, LAS float* L) {
;     ...
;     for (int r = 0; r < 4; ++r) { const f32x4 o = *(const LAS f32x4*)(L + (i0 + r) * 128 + e4);
;         float ss = (o.x * o.x + o.y * o.y) + (o.z * o.z + o.w * o.w);
; #pragma unroll
;         for (int m = 1; m < 32; m <<= 1) ss += __shfl_xor(ss, m);
;         const float rs = rsqrtf(ss * (1.f / 128.f) + EPS);
;         const size_t row = (size_t)cc * 64 + i0 + r;
;         const u32x2 gw = *(const u32x2*)(P + (size_t)(i0 + r) * INP + C_CG + h * 128 + e4);
;         const f32x4 y = o * rs * gn;
;         u32x2 w; w.x = cvt_pk_bf16(y.x * silu_f(bflo(gw.x)), y.y * silu_f(bfhi(gw.x))); w.y = cvt_pk_bf16(y.z * silu_f(bflo(gw.y)), y.w * silu_f(bfhi(gw.y)));
;         *(u32x2*)(Z + row * DM + 1536 + h * 128 + e4) = w; }
	v_pk_mul_f32 v[6:7], v[14:15], v[14:15]
	v_pk_mul_f32 v[18:19], v[12:13], v[12:13]
	s_nop 0
	v_pk_mov_b32 v[28:29], v[18:19], v[6:7] op_sel:[1,0]
	v_mov_b32_e32 v19, v7
	v_pk_add_f32 v[6:7], v[28:29], v[18:19]
	s_nop 0
	v_add_f32_e32 v6, v6, v7
	s_nop 1
	v_add_f32_dpp v6, v6, v6 quad_perm:[1,0,3,2] row_mask:0xf bank_mask:0xf
	s_nop 1
	v_add_f32_dpp v27, v6, v6 quad_perm:[2,3,0,1] row_mask:0xf bank_mask:0xf
	ds_bpermute_b32 v28, v24, v27
	v_or_b32_e32 v6, 3, v20
	v_ashrrev_i32_e32 v7, 31, v6
	v_lshlrev_b64 v[18:19], 13, v[6:7]
	v_lshl_add_u64 v[18:19], s[20:21], 0, v[18:19]
	s_waitcnt lgkmcnt(0)
	v_add_f32_e32 v7, v27, v28
	s_nop 1
	v_lshl_add_u64 v[18:19], v[18:19], 0, s[18:19]
	v_lshl_add_u64 v[18:19], v[18:19], 0, v[0:1]
	v_add_co_u32_e32 v28, vcc, s4, v10
	v_add_f32_dpp v0, v7, v7 row_mirror row_mask:0xf bank_mask:0xf
	v_mov_b32_e32 v7, v0
	v_addc_co_u32_e32 v29, vcc, 0, v11, vcc
	global_store_dwordx2 v[28:29], v[8:9], off offset:3072
	v_add_co_u32_e64 v18, s[40:41], s10, v18
	s_nop 1
	v_permlane16_swap_b32_e32 v0, v7
	v_add_f32_e32 v0, v0, v7
	v_fmamk_f32 v0, v0, 0x3c000000, v216
	v_cmp_gt_f32_e32 vcc, s26, v0
	v_mul_f32_e32 v7, 0x4b800000, v0
	v_addc_co_u32_e64 v19, s[40:41], 0, v19, s[40:41]
	v_cndmask_b32_e32 v0, v0, v7, vcc
	v_rsq_f32_e32 v0, v0
	s_mov_b32 s4, 0xb902000
	v_mul_f32_e32 v7, 0x45800000, v0
	v_cndmask_b32_e32 v0, v0, v7, vcc
	v_pk_mul_f32 v[8:9], v[12:13], v[0:1] op_sel_hi:[1,0]
	v_pk_mul_f32 v[12:13], v[14:15], v[0:1] op_sel_hi:[1,0]
	v_pk_mul_f32 v[8:9], v[2:3], v[8:9]
	v_pk_mul_f32 v[12:13], v[4:5], v[12:13]
	s_waitcnt vmcnt(1)
	v_lshlrev_b32_e32 v0, 16, v16
	v_and_b32_e32 v7, 0xffff0000, v16
	v_lshlrev_b32_e32 v14, 16, v17
	v_and_b32_e32 v15, 0xffff0000, v17
	v_mul_f32_e32 v16, 0xbfb8aa3b, v0
	v_mul_f32_e32 v17, 0xbfb8aa3b, v7
	v_mul_f32_e32 v20, 0xbfb8aa3b, v14
	v_mul_f32_e32 v27, 0xbfb8aa3b, v15
	v_exp_f32_e32 v16, v16
	v_exp_f32_e32 v17, v17
	v_exp_f32_e32 v20, v20
	v_exp_f32_e32 v27, v27
	v_add_f32_e32 v16, 1.0, v16
	v_add_f32_e32 v17, 1.0, v17
	v_add_f32_e32 v20, 1.0, v20
	v_add_f32_e32 v27, 1.0, v27
	v_rcp_f32_e32 v16, v16
	v_rcp_f32_e32 v17, v17
	v_rcp_f32_e32 v20, v20
	v_rcp_f32_e32 v27, v27
	v_mul_f32_e32 v0, v16, v0
	v_mul_f32_e32 v7, v17, v7
	v_mul_f32_e32 v14, v20, v14
	v_mul_f32_e32 v15, v27, v15
	v_mul_f32_e32 v0, v0, v8
	v_mul_f32_e32 v7, v7, v9
	v_mul_f32_e32 v8, v14, v12
	v_mul_f32_e32 v9, v15, v13
	v_cvt_pk_bf16_f32 v12, v0, v7
	v_cvt_pk_bf16_f32 v13, v8, v9
	v_mov_b64_e32 v[14:15], v[84:85]
	v_lshl_add_u32 v0, v6, 9, v22
	ds_read_b128 v[6:9], v0
	s_waitcnt lgkmcnt(0)
	v_pk_mul_f32 v[16:17], v[8:9], v[8:9]
	v_pk_mul_f32 v[18:19], v[6:7], v[6:7]
	s_nop 0
	v_pk_mov_b32 v[28:29], v[18:19], v[16:17] op_sel:[1,0]
	v_mov_b32_e32 v19, v17
	v_pk_add_f32 v[16:17], v[28:29], v[18:19]
	s_nop 0
	v_add_f32_e32 v0, v16, v17
	s_nop 1
	v_add_f32_dpp v0, v0, v0 quad_perm:[1,0,3,2] row_mask:0xf bank_mask:0xf
	s_nop 1
	v_add_f32_dpp v0, v0, v0 quad_perm:[2,3,0,1] row_mask:0xf bank_mask:0xf
	s_nop 1
	v_add_f32_dpp v0, v0, v0 row_half_mirror row_mask:0xf bank_mask:0xf
	s_nop 1
	v_add_co_u32_e64 v16, s[40:41], s4, v10
	v_add_co_u32_e32 v10, vcc, 0xb903000, v10
	v_add_f32_dpp v0, v0, v0 row_mirror row_mask:0xf bank_mask:0xf
	v_mov_b32_e32 v18, v0
	v_addc_co_u32_e64 v17, s[40:41], 0, v11, s[40:41]
	global_store_dwordx2 v[16:17], v[12:13], off offset:3072
	v_addc_co_u32_e32 v11, vcc, 0, v11, vcc
	s_nop 1
	v_permlane16_swap_b32_e32 v0, v18
	v_add_f32_e32 v0, v0, v18
	v_fmamk_f32 v0, v0, 0x3c000000, v216
	v_cmp_gt_f32_e64 s[40:41], s26, v0
	v_mul_f32_e32 v18, 0x4b800000, v0
	s_nop 0
	v_cndmask_b32_e64 v0, v0, v18, s[40:41]
	v_rsq_f32_e32 v0, v0
	s_nop 0
	v_mul_f32_e32 v12, 0x45800000, v0
	v_cndmask_b32_e64 v0, v0, v12, s[40:41]
	v_pk_mul_f32 v[6:7], v[6:7], v[0:1] op_sel_hi:[1,0]
	v_pk_mul_f32 v[8:9], v[8:9], v[0:1] op_sel_hi:[1,0]
	v_pk_mul_f32 v[2:3], v[2:3], v[6:7]
	v_pk_mul_f32 v[4:5], v[4:5], v[8:9]
	s_waitcnt vmcnt(1)
	v_lshlrev_b32_e32 v0, 16, v14
	v_and_b32_e32 v6, 0xffff0000, v14
	v_lshlrev_b32_e32 v7, 16, v15
	v_and_b32_e32 v8, 0xffff0000, v15
	v_mul_f32_e32 v9, 0xbfb8aa3b, v0
	v_mul_f32_e32 v12, 0xbfb8aa3b, v6
	v_mul_f32_e32 v13, 0xbfb8aa3b, v7
	v_mul_f32_e32 v14, 0xbfb8aa3b, v8
	v_exp_f32_e32 v9, v9
	v_exp_f32_e32 v12, v12
	v_exp_f32_e32 v13, v13
	v_exp_f32_e32 v14, v14
	v_add_f32_e32 v9, 1.0, v9
	v_add_f32_e32 v12, 1.0, v12
	v_add_f32_e32 v13, 1.0, v13
	v_add_f32_e32 v14, 1.0, v14
	v_rcp_f32_e32 v9, v9
	v_rcp_f32_e32 v12, v12
	v_rcp_f32_e32 v13, v13
	v_rcp_f32_e32 v14, v14
	v_mul_f32_e32 v0, v9, v0
	v_mul_f32_e32 v6, v12, v6
	v_mul_f32_e32 v7, v13, v7
	v_mul_f32_e32 v8, v14, v8
	v_mul_f32_e32 v0, v0, v2
	v_mul_f32_e32 v2, v6, v3
	v_mul_f32_e32 v3, v7, v4
	v_mul_f32_e32 v4, v8, v5
	v_cvt_pk_bf16_f32 v2, v0, v2
	v_cvt_pk_bf16_f32 v3, v3, v4
	global_store_dwordx2 v[10:11], v[2:3], off offset:3072
	s_branch .LBB0_70
